# v040
# baseline (speedup 1.0000x reference)
.Lmy_skip_pop:
	v_mov_b32_e32 v0, s51
	s_waitcnt lgkmcnt(0)
	s_barrier
	ds_read_b32 v0, v0
	s_waitcnt lgkmcnt(0)
	v_cmp_gt_i32_e32 vcc, 0, v0
	v_readfirstlane_b32 s2, v0
	s_cbranch_vccnz .LBB0_340
	s_mul_hi_u32 s3, s2, 0xaaaaaaab
	s_lshr_b32 s3, s3, 8
	s_mul_i32 s5, s3, 0x180
	s_sub_i32 s5, s2, s5
	s_lshr_b32 s7, s5, 2
	s_and_b32 s7, s7, 0x78
	s_sub_i32 s8, s7, s3
	s_and_b32 s2, s5, 32
	s_add_i32 s8, s8, 7
	s_add_i32 s7, s7, s3
	s_cmp_eq_u32 s2, 0
	s_cselect_b32 s3, s7, s8
	s_mul_hi_i32 s7, s3, 0x2aaaaaab
	s_lshr_b32 s8, s7, 31
	s_mul_hi_i32 s21, s3, 0xd5555555
	s_add_i32 s7, s7, s8
	s_lshr_b32 s2, s21, 31
	s_mul_i32 s7, s7, 6
	s_add_i32 s21, s21, s2
	s_sub_i32 s3, s3, s7
	s_add_i32 s2, s21, 15
	s_and_b32 s5, s5, 31
	s_lshl_b32 s7, s3, 5
	s_cmp_lt_i32 s3, 4
	s_cselect_b32 s7, s7, 0
	s_lshl_b32 s8, s2, 4
	s_add_i32 s8, s8, 0
	s_add_i32 s8, s8, 0x20000
	v_mov_b32_e32 v0, s8
	s_max_i32 s3, s3, 3
	s_waitcnt vmcnt(0)
	ds_read_b96 v[2:4], v0
	s_or_b32 s22, s5, s7
	s_add_i32 s18, s3, -3
	s_cmp_eq_u32 s18, 1
	s_movk_i32 s3, 0x5000
	v_readfirstlane_b32 s9, v195
	s_cselect_b32 s25, 0x4000, s3
	s_bfe_u32 s5, s9, 0x20006
	s_lshl_b32 s10, s22, 7
	s_lshl_b32 s11, s5, 5
	s_lshr_b32 s3, s9, 6
	s_lshr_b32 s7, s9, 8
	s_or_b32 s23, s11, s10
	s_mul_i32 s12, s2, 0x600000
	s_waitcnt lgkmcnt(0)
	v_readfirstlane_b32 s8, v2
	s_mul_hi_i32 s11, s2, 0x600000
	s_add_u32 s16, s63, s12
	s_addc_u32 s17, s4, s11
	s_sub_i32 s11, s10, s8
	s_or_b32 s24, s10, 0x7f
	s_ashr_i32 s11, s11, 6
	s_add_i32 s8, s8, s24
	s_lshl_b32 s80, s7, 7
	s_add_i32 s33, s21, 16
	s_max_i32 s11, s11, 0
	s_ashr_i32 s12, s8, 6
	s_cmpk_lt_u32 s9, 0x100
	s_cselect_b64 s[8:9], -1, 0
	s_and_b64 s[14:15], s[8:9], exec
	v_readfirstlane_b32 s13, v3
	v_readfirstlane_b32 s19, v4
	s_cselect_b32 s14, 16, 32
	v_mov_b32_e32 v0, v195
	v_mov_b32_e32 v181, v194
	s_cselect_b32 s13, s13, s19
	s_add_i32 s15, s14, s2
	s_lshl_b32 s19, s5, 11
	s_cmp_eq_u32 s18, 0
	v_and_b32_e32 v0, 31, v181
	s_cselect_b32 s14, 0, s25
	v_or_b32_e32 v10, s23, v0
	v_add_u32_e32 v164, s14, v10
	v_ashrrev_i32_e32 v165, 31, v164
	v_ashrrev_i32_e32 v186, 5, v181
	v_lshlrev_b64 v[2:3], 8, v[164:165]
	v_lshl_add_u64 v[2:3], s[16:17], 0, v[2:3]
	v_lshlrev_b32_e32 v166, 3, v186
	v_lshl_add_u64 v[2:3], v[2:3], 0, s[80:81]
	v_ashrrev_i32_e32 v167, 31, v166
	v_lshl_add_u64 v[2:3], v[166:167], 1, v[2:3]
	global_load_dwordx4 v[144:147], v[2:3], off
	global_load_dwordx4 v[148:151], v[2:3], off offset:32
	global_load_dwordx4 v[152:155], v[2:3], off offset:64
	global_load_dwordx4 v[156:159], v[2:3], off offset:96
	v_lshlrev_b32_e32 v3, 2, v181
	v_lshl_add_u32 v2, s7, 3, v186
	v_and_b32_e32 v3, 12, v3
	v_bfe_u32 v4, v181, 2, 2
	v_lshlrev_b32_e32 v0, 8, v0
	v_bitop3_b32 v5, v3, v2, v4 bitop3:0x36
	v_lshl_add_u32 v182, v5, 4, v0
	v_add_u32_e32 v5, 2, v2
	v_bitop3_b32 v5, v3, v5, v4 bitop3:0x36
	v_lshl_add_u32 v183, v5, 4, v0
	v_add_u32_e32 v5, 4, v2
	v_add_u32_e32 v2, 6, v2
	v_bitop3_b32 v5, v3, v5, v4 bitop3:0x36
	v_bitop3_b32 v2, v3, v2, v4 bitop3:0x36
	v_lshl_add_u32 v184, v5, 4, v0
	v_lshl_add_u32 v185, v2, 4, v0
	v_ashrrev_i32_e32 v0, 4, v181
	v_lshlrev_b32_e32 v3, 1, v0
	v_and_b32_e32 v7, 12, v181
	v_lshlrev_b32_e32 v11, 2, v186
	v_and_b32_e32 v3, 2, v3
	v_bfe_u32 v5, v181, 1, 1
	v_lshlrev_b32_e32 v8, 3, v181
	v_and_or_b32 v9, v186, 3, v7
	v_or_b32_e32 v6, v3, v5
	v_and_b32_e32 v12, 8, v8
	v_or_b32_e32 v8, v11, v4
	v_bitop3_b32 v3, v3, v9, v5 bitop3:0x36
	v_lshlrev_b32_e32 v8, 8, v8
	v_lshlrev_b32_e32 v3, 4, v3
	v_or3_b32 v187, v3, v8, v12
	v_add_u32_e32 v3, 8, v11
	v_or_b32_e32 v4, v3, v4
	v_bfe_u32 v3, v3, 2, 2
	v_lshlrev_b32_e32 v13, 8, v4
	v_bitop3_b32 v4, v3, v6, v7 bitop3:0x36
	v_lshlrev_b32_e32 v4, 4, v4
	v_or3_b32 v188, v4, v13, v12
	v_or_b32_e32 v4, 4, v6
	v_bitop3_b32 v4, v3, v4, v7 bitop3:0x36
	v_bitop3_b32 v5, v6, v9, 4 bitop3:0x36
	v_lshlrev_b32_e32 v4, 4, v4
	v_lshlrev_b32_e32 v5, 4, v5
	v_or3_b32 v190, v4, v13, v12
	v_or_b32_e32 v4, 8, v6
	v_or3_b32 v189, v5, v8, v12
	v_bitop3_b32 v5, v6, v9, 8 bitop3:0x36
	v_bitop3_b32 v4, v3, v4, v7 bitop3:0x36
	v_lshlrev_b32_e32 v5, 4, v5
	v_lshlrev_b32_e32 v4, 4, v4
	v_or3_b32 v191, v5, v8, v12
	v_or3_b32 v192, v4, v13, v12
	v_or_b32_e32 v4, 12, v6
	v_bitop3_b32 v5, v6, v9, 12 bitop3:0x36
	v_cvt_f32_i32_e32 v6, s33
	v_and_b32_e32 v2, 15, v181
	v_bitop3_b32 v14, v3, v4, v7 bitop3:0x36
	v_lshlrev_b32_e32 v5, 4, v5
	v_mul_f32_e32 v3, -0.5, v6
	v_exp_f32_e32 v15, v3
	v_lshl_add_u32 v3, v0, 7, s19
	v_lshlrev_b32_e32 v0, 5, v0
	v_lshlrev_b32_e32 v2, 3, v2
	v_or3_b32 v193, v5, v8, v12
	v_xor_b32_e32 v5, v0, v2
	v_xor_b32_e32 v2, 8, v5
	s_movk_i32 s17, 0x200
	v_add3_u32 v2, v3, v2, s17
	v_xor_b32_e32 v4, 16, v5
	s_movk_i32 s17, 0x400
	v_add_u32_e32 v0, v3, v5
	v_add3_u32 v4, v3, v4, s17
	v_xor_b32_e32 v5, 24, v5
	s_movk_i32 s17, 0x600
	v_add3_u32 v6, v3, v5, s17
	s_mul_hi_i32 s16, s15, 0x600000
	s_mul_i32 s15, s15, 0x600000
	s_cselect_b32 s17, 0xff, 63
	s_add_u32 s15, s63, s15
	s_addc_u32 s16, s4, s16
	s_lshl_b32 s14, s14, 8
	s_add_u32 s33, s15, s14
	s_addc_u32 s37, s16, 0
	s_lshr_b32 s44, s11, 1
	s_ashr_i32 s11, s10, 31
	s_lshl_b64 s[14:15], s[10:11], 8
	s_add_u32 s14, s33, s14
	s_addc_u32 s15, s37, s15
	s_lshl_b32 s11, s7, 14
	s_add_i32 s45, s11, 0
	s_lshl_b32 s11, s5, 12
	s_add_i32 s45, s45, s11
	v_lshlrev_b32_e32 v168, 1, v0
	v_lshlrev_b32_e32 v170, 1, v2
	v_lshlrev_b32_e32 v172, 1, v4
	v_lshlrev_b32_e32 v174, 1, v6
	v_mov_b32_e32 v169, v1
	v_mov_b32_e32 v171, v1
	v_mov_b32_e32 v173, v1
	v_mov_b32_e32 v175, v1
	s_mov_b32 m0, s45
	s_nop 0
	global_load_lds_dwordx4 v168, s[14:15]
	s_add_i32 m0, s45, 0x400
	s_nop 0
	global_load_lds_dwordx4 v170, s[14:15]
	s_add_i32 m0, s45, 0x800
	s_nop 0
	global_load_lds_dwordx4 v172, s[14:15]
	s_add_i32 m0, s45, 0xc00
	s_nop 0
	global_load_lds_dwordx4 v174, s[14:15]
	s_add_u32 s14, s14, 0x4000
	s_addc_u32 s15, s15, 0
	s_add_i32 m0, s45, 0x8000
	s_nop 0
	global_load_lds_dwordx4 v168, s[14:15]
	s_add_i32 m0, s45, 0x8400
	s_nop 0
	global_load_lds_dwordx4 v170, s[14:15]
	s_add_i32 m0, s45, 0x8800
	s_nop 0
	global_load_lds_dwordx4 v172, s[14:15]
	s_add_i32 m0, s45, 0x8c00
	s_nop 0
	global_load_lds_dwordx4 v174, s[14:15]
	s_waitcnt vmcnt(10)
	v_and_b32_e32 v7, 0xffff0000, v148
	v_and_b32_e32 v5, 0xffff0000, v144
	v_lshlrev_b32_e32 v3, 16, v144
	v_mul_f32_e32 v5, v5, v5
	v_fmac_f32_e32 v5, v3, v3
	v_lshlrev_b32_e32 v3, 16, v145
	v_fmac_f32_e32 v5, v3, v3
	v_and_b32_e32 v3, 0xffff0000, v145
	v_fmac_f32_e32 v5, v3, v3
	v_lshlrev_b32_e32 v3, 16, v146
	v_fmac_f32_e32 v5, v3, v3
	v_and_b32_e32 v3, 0xffff0000, v146
	v_fmac_f32_e32 v5, v3, v3
	v_lshlrev_b32_e32 v3, 16, v147
	v_fmac_f32_e32 v5, v3, v3
	v_and_b32_e32 v3, 0xffff0000, v147
	v_fmac_f32_e32 v5, v3, v3
	v_lshlrev_b32_e32 v3, 16, v148
	v_mul_f32_e32 v7, v7, v7
	v_fmac_f32_e32 v7, v3, v3
	v_lshlrev_b32_e32 v3, 16, v149
	v_fmac_f32_e32 v7, v3, v3
	v_and_b32_e32 v3, 0xffff0000, v149
	v_fmac_f32_e32 v7, v3, v3
	v_lshlrev_b32_e32 v3, 16, v150
	v_fmac_f32_e32 v7, v3, v3
	v_and_b32_e32 v3, 0xffff0000, v150
	v_fmac_f32_e32 v7, v3, v3
	v_lshlrev_b32_e32 v3, 16, v151
	v_fmac_f32_e32 v7, v3, v3
	v_and_b32_e32 v3, 0xffff0000, v151
	v_fmac_f32_e32 v7, v3, v3
	v_add_f32_e32 v3, v5, v7
	s_waitcnt vmcnt(9)
	v_and_b32_e32 v7, 0xffff0000, v152
	v_lshlrev_b32_e32 v5, 16, v152
	v_mul_f32_e32 v7, v7, v7
	v_fmac_f32_e32 v7, v5, v5
	v_lshlrev_b32_e32 v5, 16, v153
	v_fmac_f32_e32 v7, v5, v5
	v_and_b32_e32 v5, 0xffff0000, v153
	v_fmac_f32_e32 v7, v5, v5
	v_lshlrev_b32_e32 v5, 16, v154
	v_fmac_f32_e32 v7, v5, v5
	v_and_b32_e32 v5, 0xffff0000, v154
	v_fmac_f32_e32 v7, v5, v5
	v_lshlrev_b32_e32 v5, 16, v155
	v_fmac_f32_e32 v7, v5, v5
	v_and_b32_e32 v5, 0xffff0000, v155
	v_fmac_f32_e32 v7, v5, v5
	s_waitcnt vmcnt(8)
	v_and_b32_e32 v5, 0xffff0000, v156
	v_add_f32_e32 v16, v3, v7
	v_lshlrev_b32_e32 v3, 16, v156
	v_mul_f32_e32 v17, v5, v5
	v_fmac_f32_e32 v17, v3, v3
	v_lshlrev_b32_e32 v3, 16, v157
	v_fmac_f32_e32 v17, v3, v3
	v_and_b32_e32 v3, 0xffff0000, v157
	v_fmac_f32_e32 v17, v3, v3
	v_lshlrev_b32_e32 v3, 16, v158
	v_fmac_f32_e32 v17, v3, v3
	v_mov_b32_e32 v3, v1
	v_mov_b32_e32 v5, v1
	v_mov_b32_e32 v7, v1
	v_and_b32_e32 v0, 0xffff0000, v158
	v_fmac_f32_e32 v17, v0, v0
	v_lshlrev_b32_e32 v0, 16, v159
	v_fmac_f32_e32 v17, v0, v0
	v_and_b32_e32 v0, 0xffff0000, v159
	v_fmac_f32_e32 v17, v0, v0
	v_add_f32_e32 v0, v16, v17
	v_mov_b32_e32 v2, v0
	s_nop 1
	v_permlane32_swap_b32_e32 v0, v2
	v_add_f32_e32 v0, v0, v2
	v_mul_f32_e32 v2, 0x4f800000, v0
	v_cmp_gt_f32_e32 vcc, s65, v0
	v_lshlrev_b32_e32 v3, 4, v14
	v_or3_b32 v196, v3, v13, v12
	v_cndmask_b32_e32 v0, v0, v2, vcc
	v_sqrt_f32_e32 v2, v0
	s_min_i32 s11, s17, s12
	s_ashr_i32 s46, s11, 1
	s_lshl_b32 s11, s3, 2
	v_add_u32_e32 v3, -1, v2
	v_fma_f32 v4, -v3, v2, v0
	v_cmp_ge_f32_e64 s[38:39], 0, v4
	v_add_u32_e32 v4, 1, v2
	s_add_i32 s48, s11, 0
	v_cndmask_b32_e64 v3, v2, v3, s[38:39]
	v_fma_f32 v2, -v4, v2, v0
	v_cmp_lt_f32_e64 s[38:39], 0, v2
	s_or_b32 s47, s23, 31
	s_add_i32 s48, s48, 0x20440
	v_cndmask_b32_e64 v2, v3, v4, s[38:39]
	v_mul_f32_e32 v3, 0x37800000, v2
	v_cndmask_b32_e32 v2, v2, v3, vcc
	v_cmp_class_f32_e32 vcc, v0, v227
	s_add_i32 s49, s22, 1
	s_cmp_lt_i32 s22, s46
	v_cndmask_b32_e32 v0, v2, v0, vcc
	v_mul_f32_e32 v176, 0x3fb8aa3b, v15
	v_mul_f32_e32 v0, 0x3e3a82f9, v0
	s_cselect_b32 s11, s49, -1
	s_add_i32 s12, s22, -1
	s_or_b32 s50, s10, 1
	v_mov_b32_e32 v14, v1
	v_mov_b32_e32 v15, v1
	v_mul_f32_e32 v197, s13, v0
	v_sub_u32_e32 v198, v11, v10
	v_xor_b32_e32 v178, 0x80000000, v176
	s_cmp_gt_i32 s22, s44
	v_mov_b32_e32 v0, v1
	v_mov_b32_e32 v2, v1
	v_mov_b32_e32 v3, v1
	v_mov_b32_e32 v4, v1
	v_mov_b32_e32 v6, v1
	v_mov_b32_e32 v8, v1
	v_mov_b32_e32 v9, v1
	v_mov_b32_e32 v10, v1
	v_mov_b32_e32 v11, v1
	v_mov_b32_e32 v12, v1
	v_mov_b32_e32 v13, v1
	v_mov_b64_e32 v[30:31], v[14:15]
	v_mov_b64_e32 v[46:47], v[14:15]
	v_mov_b64_e32 v[62:63], v[14:15]
	v_mov_b64_e32 v[78:79], v[14:15]
	s_mov_b32 s25, 0
	v_cmp_eq_u32_e64 s[38:39], 0, v181
	s_cselect_b32 s79, s12, s11
	s_cselect_b32 s78, 1, 2
	v_mov_b32_e32 v177, v176
	v_mov_b32_e32 v179, v178
	v_mul_f32_e32 v201, 0xc27c0000, v176
	v_add_f32_e32 v201, 0x41000000, v201
	s_nop 0
	v_readfirstlane_b32 s100, v201
	v_mov_b32_e32 v201, 0
	v_mov_b32_e32 v199, 0
	s_mov_b32 s83, 0
	v_mov_b32_e32 v180, 0
	v_mov_b64_e32 v[28:29], v[12:13]
	v_mov_b64_e32 v[26:27], v[10:11]
	v_mov_b64_e32 v[24:25], v[8:9]
	v_mov_b64_e32 v[22:23], v[6:7]
	v_mov_b64_e32 v[20:21], v[4:5]
	v_mov_b64_e32 v[18:19], v[2:3]
	v_mov_b64_e32 v[16:17], v[0:1]
	v_mov_b64_e32 v[44:45], v[12:13]
	v_mov_b64_e32 v[42:43], v[10:11]
	v_mov_b64_e32 v[40:41], v[8:9]
	v_mov_b64_e32 v[38:39], v[6:7]
	v_mov_b64_e32 v[36:37], v[4:5]
	v_mov_b64_e32 v[34:35], v[2:3]
	v_mov_b64_e32 v[32:33], v[0:1]
	v_mov_b64_e32 v[60:61], v[12:13]
	v_mov_b64_e32 v[58:59], v[10:11]
	v_mov_b64_e32 v[56:57], v[8:9]
	v_mov_b64_e32 v[54:55], v[6:7]
	v_mov_b64_e32 v[52:53], v[4:5]
	v_mov_b64_e32 v[50:51], v[2:3]
	v_mov_b64_e32 v[48:49], v[0:1]
	v_mov_b64_e32 v[76:77], v[12:13]
	v_mov_b64_e32 v[74:75], v[10:11]
	v_mov_b64_e32 v[72:73], v[8:9]
	v_mov_b64_e32 v[70:71], v[6:7]
	v_mov_b64_e32 v[68:69], v[4:5]
	v_mov_b64_e32 v[66:67], v[2:3]
	v_mov_b64_e32 v[64:65], v[0:1]
	s_mov_b32 s18, s22
	s_mov_b32 s10, 0
	v_readfirstlane_b32 s101, v195
	s_cmpk_lt_u32 s101, 0x100
	s_cbranch_scc1 .Lmy_prio_lo
	s_setprio 1
